# phase G norm: gain/shift/scale fetches issued ahead of the wave reduction
# speedup vs baseline: 1.0543x; 1.0027x over previous
; DI unsigned cvt_pk_bf16(float lo, float hi) { f32x2_t v = {lo, hi}; bf16x2_t b = __builtin_convertvector(v, bf16x2_t); return __builtin_bit_cast(unsigned, b); }
; DI void phase_norm(const Params& p, int l, const float* g, int shift_idx, bool skip_ctx, bool from_input) {
;     ...
;       float ss = 0.f;
; #pragma unroll
;       for (int i = 0; i < 4; ++i) ss += v[u][i][0] * v[u][i][0] + v[u][i][1] * v[u][i][1] + v[u][i][2] * v[u][i][2] + v[u][i][3] * v[u][i][3];
;       ss = wave_sum(ss);
;       const float rs = rsqrtf(ss * (1.f / 1024.f) + EPS);
;       const float* mr = mod + (size_t)(t < CTXL ? 8 : b) * 6144 + shift_idx * 1024;
; #pragma unroll
;       for (int i = 0; i < 4; ++i) {
;         const int col = lane * 4 + i * 256;
;         const f32x4 gg = *(const f32x4*)(g + col), sh = *(const f32x4*)(mr + col), scl = *(const f32x4*)(mr + 1024 + col);
;         f32x4 y = (v[u][i] * rs) * gg;
;         y = y * (scl + 1.f) + sh;
;         u32x2 pk; pk.x = cvt_pk_bf16(y[0], y[1]); pk.y = cvt_pk_bf16(y[2], y[3]);
;         *(u32x2*)(hb + (size_t)row * 1024 + col) = pk;
;       }
.LBB0_1487:
	s_or_b64 exec, exec, s[42:43]
	v_lshlrev_b32_e32 v0, 2, v40
	v_lshlrev_b32_e32 v56, 2, v44
	v_lshlrev_b32_e32 v54, 2, v46
	v_lshlrev_b32_e32 v52, 2, v48
	s_and_saveexec_b64 s[42:43], s[44:45]
	s_cbranch_execz .LBB0_1489
	s_waitcnt vmcnt(0)
	v_mov_b32_e32 v60, v27
	v_mov_b32_e32 v61, v31
	v_mov_b32_e32 v36, v26
	v_mov_b32_e32 v37, v30
	v_pk_mul_f32 v[60:61], v[60:61], v[60:61]
	v_mov_b32_e32 v62, v19
	v_pk_fma_f32 v[36:37], v[36:37], v[36:37], v[60:61]
	v_mov_b32_e32 v60, v28
	v_mov_b32_e32 v61, v32
	v_pk_fma_f32 v[36:37], v[60:61], v[60:61], v[36:37]
	v_mov_b32_e32 v60, v29
	v_mov_b32_e32 v61, v33
	v_mov_b32_e32 v63, v23
	v_pk_fma_f32 v[36:37], v[60:61], v[60:61], v[36:37]
	v_mov_b32_e32 v60, v18
	v_mov_b32_e32 v61, v22
	v_pk_mul_f32 v[62:63], v[62:63], v[62:63]
	v_add_f32_e32 v36, v36, v37
	v_pk_fma_f32 v[60:61], v[60:61], v[60:61], v[62:63]
	v_mov_b32_e32 v62, v20
	v_mov_b32_e32 v63, v24
	v_pk_fma_f32 v[60:61], v[62:63], v[62:63], v[60:61]
	v_mov_b32_e32 v62, v21
	v_mov_b32_e32 v63, v25
	v_pk_fma_f32 v[60:61], v[62:63], v[62:63], v[60:61]
	s_movk_i32 s18, 0xff
	v_add_f32_e32 v36, v61, v36
	v_add_f32_e32 v36, v60, v36
	ds_bpermute_b32 v37, v197, v36
	v_ashrrev_i32_e32 v39, 31, v38
	v_lshlrev_b64 v[76:77], 11, v[38:39]
	v_mov_b32_e32 v57, v1
	v_mov_b32_e32 v55, v1
	s_waitcnt lgkmcnt(0)
	v_add_f32_e32 v36, v36, v37
	v_cmp_lt_i32_e32 vcc, s18, v35
	s_mov_b64 s[18:19], 0x1000
	v_cndmask_b32_e32 v122, 8, v34, vcc
	v_mul_hi_i32_i24_e32 v123, 0x6000, v122
	v_mul_i32_i24_e32 v122, 0x6000, v122
	v_lshl_add_u64 v[64:65], s[4:5], 0, v[122:123]
	v_lshl_add_u64 v[62:63], v[64:65], 0, s[18:19]
	v_lshl_add_u64 v[66:67], v[64:65], 0, v[0:1]
	v_lshl_add_u64 v[64:65], v[62:63], 0, v[0:1]
	global_load_dwordx4 v[122:125], v[42:43], off
	global_load_dwordx4 v[68:71], v[66:67], off
	global_load_dwordx4 v[72:75], v[64:65], off
	global_load_dwordx4 v[80:83], v[42:43], off offset:1024
	global_load_dwordx4 v[84:87], v[66:67], off offset:1024
	v_mov_b32_e32 v57, v1
	v_lshl_add_u64 v[116:117], v[62:63], 0, v[56:57]
	global_load_dwordx4 v[88:91], v[116:117], off
	global_load_dwordx4 v[92:95], v[42:43], off offset:2048
	global_load_dwordx4 v[96:99], v[66:67], off offset:2048
	v_mov_b32_e32 v55, v1
	v_lshl_add_u64 v[118:119], v[62:63], 0, v[54:55]
	global_load_dwordx4 v[100:103], v[118:119], off
	global_load_dwordx4 v[104:107], v[42:43], off offset:3072
	global_load_dwordx4 v[108:111], v[66:67], off offset:3072
	v_mov_b32_e32 v53, v1
	v_lshl_add_u64 v[120:121], v[62:63], 0, v[52:53]
	global_load_dwordx4 v[112:115], v[120:121], off
	ds_bpermute_b32 v37, v198, v36
	v_mov_b32_e32 v53, v1
	s_waitcnt lgkmcnt(0)
	v_add_f32_e32 v36, v36, v37
	ds_bpermute_b32 v37, v199, v36
	s_waitcnt lgkmcnt(0)
	v_add_f32_e32 v36, v36, v37
	ds_bpermute_b32 v37, v200, v36
	s_waitcnt lgkmcnt(0)
	v_add_f32_e32 v36, v36, v37
	ds_bpermute_b32 v37, v201, v36
	s_waitcnt lgkmcnt(0)
	v_add_f32_e32 v36, v36, v37
	ds_bpermute_b32 v37, v202, v36
	s_waitcnt lgkmcnt(0)
	v_add_f32_e32 v36, v36, v37
	v_fmamk_f32 v36, v36, 0x3a800000, v148
	v_cmp_gt_f32_e32 vcc, s2, v36
	v_mul_f32_e32 v37, 0x4b800000, v36
	s_nop 0
	v_cndmask_b32_e32 v36, v36, v37, vcc
	v_rsq_f32_e32 v36, v36
	s_nop 0
	v_mul_f32_e32 v37, 0x45800000, v36
	v_cndmask_b32_e32 v60, v36, v37, vcc
	v_pk_mul_f32 v[32:33], v[32:33], v[60:61] op_sel_hi:[1,0]
	v_pk_mul_f32 v[30:31], v[30:31], v[60:61] op_sel_hi:[1,0]
	v_lshl_add_u64 v[64:65], v[50:51], 0, v[76:77]
	v_pk_mul_f32 v[28:29], v[28:29], v[60:61] op_sel_hi:[1,0]
	v_pk_mul_f32 v[26:27], v[26:27], v[60:61] op_sel_hi:[1,0]
	v_pk_mul_f32 v[24:25], v[24:25], v[60:61] op_sel_hi:[1,0]
	v_pk_mul_f32 v[22:23], v[22:23], v[60:61] op_sel_hi:[1,0]
	v_pk_mul_f32 v[20:21], v[20:21], v[60:61] op_sel_hi:[1,0]
	v_pk_mul_f32 v[18:19], v[18:19], v[60:61] op_sel_hi:[1,0]
	s_waitcnt vmcnt(2)
	v_pk_mul_f32 v[30:31], v[122:123], v[30:31]
	v_pk_mul_f32 v[32:33], v[124:125], v[32:33]
	s_waitcnt vmcnt(0)
	v_pk_add_f32 v[122:123], v[74:75], 1.0 op_sel_hi:[1,0]
	v_pk_add_f32 v[124:125], v[72:73], 1.0 op_sel_hi:[1,0]
	v_pk_fma_f32 v[32:33], v[122:123], v[32:33], v[70:71]
	v_pk_fma_f32 v[30:31], v[124:125], v[30:31], v[68:69]
	v_lshl_add_u64 v[68:69], v[62:63], 0, v[56:57]
	v_cvt_pk_bf16_f32 v30, v30, v31
	v_cvt_pk_bf16_f32 v31, v32, v33
	global_store_dwordx2 v[64:65], v[30:31], off
	v_mov_b32_e32 v34, v80
	v_mov_b32_e32 v35, v81
	v_mov_b32_e32 v36, v82
	v_mov_b32_e32 v37, v83
	s_nop 0
	v_mov_b32_e32 v30, v84
	v_mov_b32_e32 v31, v85
	v_mov_b32_e32 v32, v86
	v_mov_b32_e32 v33, v87
	v_pk_mul_f32 v[26:27], v[34:35], v[26:27]
	v_mov_b32_e32 v68, v88
	v_mov_b32_e32 v69, v89
	v_mov_b32_e32 v70, v90
	v_mov_b32_e32 v71, v91
	v_pk_mul_f32 v[28:29], v[36:37], v[28:29]
	v_pk_add_f32 v[34:35], v[70:71], 1.0 op_sel_hi:[1,0]
	v_pk_add_f32 v[36:37], v[68:69], 1.0 op_sel_hi:[1,0]
	v_pk_fma_f32 v[28:29], v[34:35], v[28:29], v[32:33]
	v_pk_fma_f32 v[26:27], v[36:37], v[26:27], v[30:31]
	v_lshl_add_u64 v[34:35], v[62:63], 0, v[54:55]
	v_cvt_pk_bf16_f32 v26, v26, v27
	v_cvt_pk_bf16_f32 v27, v28, v29
	global_store_dwordx2 v[64:65], v[26:27], off offset:512
	v_mov_b32_e32 v26, v92
	v_mov_b32_e32 v27, v93
	v_mov_b32_e32 v28, v94
	v_mov_b32_e32 v29, v95
	s_nop 0
	v_mov_b32_e32 v30, v96
	v_mov_b32_e32 v31, v97
	v_mov_b32_e32 v32, v98
	v_mov_b32_e32 v33, v99
	v_pk_mul_f32 v[22:23], v[26:27], v[22:23]
	v_mov_b32_e32 v34, v100
	v_mov_b32_e32 v35, v101
	v_mov_b32_e32 v36, v102
	v_mov_b32_e32 v37, v103
	v_pk_mul_f32 v[24:25], v[28:29], v[24:25]
	v_pk_add_f32 v[26:27], v[36:37], 1.0 op_sel_hi:[1,0]
	v_pk_add_f32 v[28:29], v[34:35], 1.0 op_sel_hi:[1,0]
	v_pk_fma_f32 v[24:25], v[26:27], v[24:25], v[32:33]
	v_pk_fma_f32 v[22:23], v[28:29], v[22:23], v[30:31]
	v_lshl_add_u64 v[30:31], v[62:63], 0, v[52:53]
	v_cvt_pk_bf16_f32 v22, v22, v23
	v_cvt_pk_bf16_f32 v23, v24, v25
	global_store_dwordx2 v[64:65], v[22:23], off offset:1024
	v_mov_b32_e32 v22, v104
	v_mov_b32_e32 v23, v105
	v_mov_b32_e32 v24, v106
	v_mov_b32_e32 v25, v107
	s_nop 0
	v_mov_b32_e32 v26, v108
	v_mov_b32_e32 v27, v109
	v_mov_b32_e32 v28, v110
	v_mov_b32_e32 v29, v111
	v_pk_mul_f32 v[18:19], v[18:19], v[22:23]
	v_mov_b32_e32 v30, v112
	v_mov_b32_e32 v31, v113
	v_mov_b32_e32 v32, v114
	v_mov_b32_e32 v33, v115
	v_pk_mul_f32 v[20:21], v[20:21], v[24:25]
	v_pk_add_f32 v[22:23], v[32:33], 1.0 op_sel_hi:[1,0]
	v_pk_add_f32 v[24:25], v[30:31], 1.0 op_sel_hi:[1,0]
	v_pk_fma_f32 v[20:21], v[20:21], v[22:23], v[28:29]
	v_pk_fma_f32 v[18:19], v[18:19], v[24:25], v[26:27]
	s_nop 0
	v_cvt_pk_bf16_f32 v18, v18, v19
	v_cvt_pk_bf16_f32 v19, v20, v21
	global_store_dwordx2 v[64:65], v[18:19], off offset:1536
; DI unsigned cvt_pk_bf16(float lo, float hi) { f32x2_t v = {lo, hi}; bf16x2_t b = __builtin_convertvector(v, bf16x2_t); return __builtin_bit_cast(unsigned, b); }
; DI void phase_norm(const Params& p, int l, const float* g, int shift_idx, bool skip_ctx, bool from_input) {
;     ...
;       float ss = 0.f;
; #pragma unroll
;       for (int i = 0; i < 4; ++i) ss += v[u][i][0] * v[u][i][0] + v[u][i][1] * v[u][i][1] + v[u][i][2] * v[u][i][2] + v[u][i][3] * v[u][i][3];
;       ss = wave_sum(ss);
;       const float rs = rsqrtf(ss * (1.f / 1024.f) + EPS);
;       const float* mr = mod + (size_t)(t < CTXL ? 8 : b) * 6144 + shift_idx * 1024;
; #pragma unroll
;       for (int i = 0; i < 4; ++i) {
;         const int col = lane * 4 + i * 256;
;         const f32x4 gg = *(const f32x4*)(g + col), sh = *(const f32x4*)(mr + col), scl = *(const f32x4*)(mr + 1024 + col);
;         f32x4 y = (v[u][i] * rs) * gg;
;         y = y * (scl + 1.f) + sh;
;         u32x2 pk; pk.x = cvt_pk_bf16(y[0], y[1]); pk.y = cvt_pk_bf16(y[2], y[3]);
;         *(u32x2*)(hb + (size_t)row * 1024 + col) = pk;
;       }
.LBB0_1489:
	s_or_b64 exec, exec, s[42:43]
	s_and_saveexec_b64 s[42:43], s[40:41]
	s_cbranch_execz .LBB0_1470
	s_waitcnt vmcnt(0)
	v_mov_b32_e32 v20, v11
	v_mov_b32_e32 v21, v15
	v_mov_b32_e32 v18, v10
	v_mov_b32_e32 v19, v14
	v_pk_mul_f32 v[20:21], v[20:21], v[20:21]
	v_mov_b32_e32 v22, v3
	v_pk_fma_f32 v[18:19], v[18:19], v[18:19], v[20:21]
	v_mov_b32_e32 v20, v12
	v_mov_b32_e32 v21, v16
	v_pk_fma_f32 v[18:19], v[20:21], v[20:21], v[18:19]
	v_mov_b32_e32 v20, v13
	v_mov_b32_e32 v21, v17
	v_mov_b32_e32 v23, v7
	v_pk_fma_f32 v[18:19], v[20:21], v[20:21], v[18:19]
	v_mov_b32_e32 v20, v2
	v_mov_b32_e32 v21, v6
	v_pk_mul_f32 v[22:23], v[22:23], v[22:23]
	v_add_f32_e32 v18, v18, v19
	v_pk_fma_f32 v[20:21], v[20:21], v[20:21], v[22:23]
	v_mov_b32_e32 v22, v4
	v_mov_b32_e32 v23, v8
	v_pk_fma_f32 v[20:21], v[22:23], v[22:23], v[20:21]
	v_mov_b32_e32 v22, v5
	v_mov_b32_e32 v23, v9
	v_pk_fma_f32 v[20:21], v[22:23], v[22:23], v[20:21]
	v_add_u32_e32 v24, v45, v41
	v_add_f32_e32 v18, v21, v18
	v_add_f32_e32 v18, v20, v18
	ds_bpermute_b32 v20, v197, v18
	v_mul_i32_i24_e32 v25, 0xfffff700, v24
	v_add3_u32 v19, s86, v25, v38
	s_movk_i32 s18, 0xff
	v_ashrrev_i32_e32 v59, 31, v58
	s_waitcnt lgkmcnt(0)
	v_add_f32_e32 v18, v18, v20
	v_cmp_lt_i32_e32 vcc, s18, v19
	s_mov_b64 s[18:19], 0x1000
	v_cndmask_b32_e32 v130, 8, v24, vcc
	v_mul_hi_i32_i24_e32 v131, 0x6000, v130
	v_mul_i32_i24_e32 v130, 0x6000, v130
	v_lshl_add_u64 v[26:27], s[4:5], 0, v[130:131]
	v_lshl_add_u64 v[24:25], v[26:27], 0, s[18:19]
	v_lshl_add_u64 v[28:29], v[26:27], 0, v[0:1]
	v_lshl_add_u64 v[26:27], v[24:25], 0, v[0:1]
	global_load_dwordx4 v[130:133], v[42:43], off
	global_load_dwordx4 v[30:33], v[28:29], off
	global_load_dwordx4 v[34:37], v[26:27], off
	global_load_dwordx4 v[80:83], v[42:43], off offset:1024
	global_load_dwordx4 v[84:87], v[28:29], off offset:1024
	v_mov_b32_e32 v57, v1
	v_lshl_add_u64 v[116:117], v[24:25], 0, v[56:57]
	global_load_dwordx4 v[88:91], v[116:117], off
	global_load_dwordx4 v[92:95], v[42:43], off offset:2048
	global_load_dwordx4 v[96:99], v[28:29], off offset:2048
	v_mov_b32_e32 v55, v1
	v_lshl_add_u64 v[118:119], v[24:25], 0, v[54:55]
	global_load_dwordx4 v[100:103], v[118:119], off
	global_load_dwordx4 v[104:107], v[42:43], off offset:3072
	global_load_dwordx4 v[108:111], v[28:29], off offset:3072
	v_mov_b32_e32 v53, v1
	v_lshl_add_u64 v[120:121], v[24:25], 0, v[52:53]
	global_load_dwordx4 v[112:115], v[120:121], off
	ds_bpermute_b32 v20, v198, v18
	v_lshlrev_b64 v[58:59], 11, v[58:59]
	v_mov_b32_e32 v57, v1
	v_mov_b32_e32 v55, v1
	v_mov_b32_e32 v53, v1
	s_waitcnt lgkmcnt(0)
	v_add_f32_e32 v18, v18, v20
	ds_bpermute_b32 v20, v199, v18
	s_waitcnt lgkmcnt(0)
	v_add_f32_e32 v18, v18, v20
	ds_bpermute_b32 v20, v200, v18
	s_waitcnt lgkmcnt(0)
	v_add_f32_e32 v18, v18, v20
	ds_bpermute_b32 v20, v201, v18
	s_waitcnt lgkmcnt(0)
	v_add_f32_e32 v18, v18, v20
	ds_bpermute_b32 v20, v202, v18
	s_waitcnt lgkmcnt(0)
	v_add_f32_e32 v18, v18, v20
	v_fmamk_f32 v18, v18, 0x3a800000, v148
	v_cmp_gt_f32_e32 vcc, s2, v18
	v_mul_f32_e32 v20, 0x4b800000, v18
	s_nop 0
	v_cndmask_b32_e32 v18, v18, v20, vcc
	v_rsq_f32_e32 v18, v18
	s_nop 0
	v_mul_f32_e32 v20, 0x45800000, v18
	v_cndmask_b32_e32 v22, v18, v20, vcc
	v_pk_mul_f32 v[16:17], v[16:17], v[22:23] op_sel_hi:[1,0]
	v_pk_mul_f32 v[14:15], v[14:15], v[22:23] op_sel_hi:[1,0]
	v_lshl_add_u64 v[26:27], v[50:51], 0, v[58:59]
	v_pk_mul_f32 v[12:13], v[12:13], v[22:23] op_sel_hi:[1,0]
	v_pk_mul_f32 v[10:11], v[10:11], v[22:23] op_sel_hi:[1,0]
	v_pk_mul_f32 v[8:9], v[8:9], v[22:23] op_sel_hi:[1,0]
	v_pk_mul_f32 v[6:7], v[6:7], v[22:23] op_sel_hi:[1,0]
	v_pk_mul_f32 v[4:5], v[4:5], v[22:23] op_sel_hi:[1,0]
	v_pk_mul_f32 v[2:3], v[2:3], v[22:23] op_sel_hi:[1,0]
	s_waitcnt vmcnt(2)
	v_pk_mul_f32 v[14:15], v[130:131], v[14:15]
	v_pk_mul_f32 v[16:17], v[132:133], v[16:17]
	s_waitcnt vmcnt(0)
	v_pk_add_f32 v[130:131], v[36:37], 1.0 op_sel_hi:[1,0]
	v_pk_add_f32 v[132:133], v[34:35], 1.0 op_sel_hi:[1,0]
	v_pk_fma_f32 v[16:17], v[130:131], v[16:17], v[32:33]
	v_pk_fma_f32 v[14:15], v[132:133], v[14:15], v[30:31]
	v_lshl_add_u64 v[30:31], v[24:25], 0, v[56:57]
	v_cvt_pk_bf16_f32 v14, v14, v15
	v_cvt_pk_bf16_f32 v15, v16, v17
	global_store_dwordx2 v[26:27], v[14:15], off
	v_mov_b32_e32 v18, v80
	v_mov_b32_e32 v19, v81
	v_mov_b32_e32 v20, v82
	v_mov_b32_e32 v21, v83
	s_nop 0
	v_mov_b32_e32 v14, v84
	v_mov_b32_e32 v15, v85
	v_mov_b32_e32 v16, v86
	v_mov_b32_e32 v17, v87
	v_pk_mul_f32 v[10:11], v[18:19], v[10:11]
	v_mov_b32_e32 v30, v88
	v_mov_b32_e32 v31, v89
	v_mov_b32_e32 v32, v90
	v_mov_b32_e32 v33, v91
	v_pk_mul_f32 v[12:13], v[20:21], v[12:13]
	v_pk_add_f32 v[18:19], v[32:33], 1.0 op_sel_hi:[1,0]
	v_pk_add_f32 v[20:21], v[30:31], 1.0 op_sel_hi:[1,0]
	v_pk_fma_f32 v[12:13], v[18:19], v[12:13], v[16:17]
	v_pk_fma_f32 v[10:11], v[20:21], v[10:11], v[14:15]
	v_lshl_add_u64 v[18:19], v[24:25], 0, v[54:55]
	v_cvt_pk_bf16_f32 v10, v10, v11
	v_cvt_pk_bf16_f32 v11, v12, v13
	global_store_dwordx2 v[26:27], v[10:11], off offset:512
	v_mov_b32_e32 v10, v92
	v_mov_b32_e32 v11, v93
	v_mov_b32_e32 v12, v94
	v_mov_b32_e32 v13, v95
	s_nop 0
	v_mov_b32_e32 v14, v96
	v_mov_b32_e32 v15, v97
	v_mov_b32_e32 v16, v98
	v_mov_b32_e32 v17, v99
	v_pk_mul_f32 v[6:7], v[10:11], v[6:7]
	v_mov_b32_e32 v18, v100
	v_mov_b32_e32 v19, v101
	v_mov_b32_e32 v20, v102
	v_mov_b32_e32 v21, v103
	v_pk_mul_f32 v[8:9], v[12:13], v[8:9]
	v_pk_add_f32 v[10:11], v[20:21], 1.0 op_sel_hi:[1,0]
	v_pk_add_f32 v[12:13], v[18:19], 1.0 op_sel_hi:[1,0]
	v_pk_fma_f32 v[8:9], v[10:11], v[8:9], v[16:17]
	v_pk_fma_f32 v[6:7], v[12:13], v[6:7], v[14:15]
	v_lshl_add_u64 v[14:15], v[24:25], 0, v[52:53]
	v_cvt_pk_bf16_f32 v6, v6, v7
	v_cvt_pk_bf16_f32 v7, v8, v9
	global_store_dwordx2 v[26:27], v[6:7], off offset:1024
	v_mov_b32_e32 v6, v104
	v_mov_b32_e32 v7, v105
	v_mov_b32_e32 v8, v106
	v_mov_b32_e32 v9, v107
	s_nop 0
	v_mov_b32_e32 v10, v108
	v_mov_b32_e32 v11, v109
	v_mov_b32_e32 v12, v110
	v_mov_b32_e32 v13, v111
	v_pk_mul_f32 v[2:3], v[2:3], v[6:7]
	v_mov_b32_e32 v14, v112
	v_mov_b32_e32 v15, v113
	v_mov_b32_e32 v16, v114
	v_mov_b32_e32 v17, v115
	v_pk_mul_f32 v[4:5], v[4:5], v[8:9]
	v_pk_add_f32 v[6:7], v[16:17], 1.0 op_sel_hi:[1,0]
	v_pk_add_f32 v[8:9], v[14:15], 1.0 op_sel_hi:[1,0]
	v_pk_fma_f32 v[4:5], v[4:5], v[6:7], v[12:13]
	v_pk_fma_f32 v[2:3], v[2:3], v[8:9], v[10:11]
	s_nop 0
	v_cvt_pk_bf16_f32 v2, v2, v3
	v_cvt_pk_bf16_f32 v3, v4, v5
	global_store_dwordx2 v[26:27], v[2:3], off offset:1536
	s_branch .LBB0_1470
